# ret_out: backward-state tile loads issued ~270 instructions earlier into dead registers (only LDS writes wait for the K-image barrier); plus chain loop v3
# speedup vs baseline: 1.0070x; 1.0010x over previous
.LBB0_903:
	s_bfe_u32 s4, s45, 0x20005
	s_lshl_b32 s14, s4, 2
	v_mov_b32_e32 v64, s14
	global_load_dword v65, v64, s[54:55]
	s_nop 0
	global_load_dword v64, v64, s[54:55] offset:16
	s_ashr_i32 s16, s45, 7
	s_and_b32 s47, s45, 31
	s_ashr_i32 s17, s16, 31
	s_lshl_b32 s46, s47, 7
	v_mov_b32_e32 v197, v167
	v_mov_b32_e32 v195, v167
	v_mov_b32_e32 v229, v185
	s_waitcnt vmcnt(0)
	v_mul_f32_e32 v65, 0x3fb8aa3b, v65
	v_exp_f32_e32 v68, v65
	v_mul_f32_e32 v64, 0x3fb8aa3b, v64
	v_exp_f32_e32 v98, v64
	v_sub_f32_e32 v69, 1.0, v68
	v_frexp_mant_f32_e32 v72, v69
	v_cvt_f64_f32_e32 v[64:65], v69
	v_sub_f32_e32 v70, 1.0, v98
	v_add_f32_e32 v71, -1.0, v69
	v_frexp_exp_i32_f64_e32 v64, v[64:65]
	v_cmp_gt_f32_e32 vcc, s38, v72
	v_add_f32_e32 v73, -1.0, v70
	v_frexp_mant_f32_e32 v74, v70
	v_cvt_f64_f32_e32 v[66:67], v70
	v_sub_f32_e32 v75, v71, v69
	v_subbrev_co_u32_e32 v64, vcc, 0, v64, vcc
	v_sub_f32_e64 v71, -v68, v71
	v_sub_f32_e32 v65, v73, v70
	v_frexp_exp_i32_f64_e32 v66, v[66:67]
	v_add_f32_e32 v67, 1.0, v75
	v_cmp_gt_f32_e32 vcc, s38, v74
	v_sub_f32_e64 v73, -v98, v73
	v_add_f32_e32 v65, 1.0, v65
	v_subbrev_co_u32_e32 v82, vcc, 0, v66, vcc
	v_add_f32_e32 v66, v71, v67
	v_sub_u32_e32 v67, 0, v64
	v_add_f32_e32 v65, v73, v65
	v_sub_u32_e32 v71, 0, v82
	v_ldexp_f32 v69, v69, v67
	v_ldexp_f32 v66, v66, v67
	v_ldexp_f32 v67, v70, v71
	v_ldexp_f32 v65, v65, v71
	v_add_f32_e32 v70, -1.0, v69
	v_add_f32_e32 v71, 1.0, v69
	v_add_f32_e32 v74, 1.0, v70
	v_add_f32_e32 v75, -1.0, v71
	v_add_f32_e32 v72, -1.0, v67
	v_sub_f32_e32 v74, v69, v74
	v_sub_f32_e32 v69, v69, v75
	v_add_f32_e32 v73, 1.0, v67
	v_add_f32_e32 v76, 1.0, v72
	v_add_f32_e32 v74, v66, v74
	v_add_f32_e32 v66, v66, v69
	v_add_f32_e32 v77, -1.0, v73
	v_sub_f32_e32 v75, v67, v76
	v_add_f32_e32 v76, v71, v66
	v_sub_f32_e32 v67, v67, v77
	v_rcp_f32_e32 v77, v76
	v_add_f32_e32 v75, v65, v75
	v_add_f32_e32 v65, v65, v67
	v_add_f32_e32 v83, v73, v65
	v_add_f32_e32 v67, v70, v74
	v_sub_f32_e32 v73, v83, v73
	v_add_f32_e32 v69, v72, v75
	v_sub_f32_e32 v70, v67, v70
	v_sub_f32_e32 v85, v65, v73
	v_mul_f32_e32 v65, v67, v77
	v_sub_f32_e32 v71, v76, v71
	v_sub_f32_e32 v72, v69, v72
	v_sub_f32_e32 v74, v74, v70
	v_mul_f32_e32 v70, v76, v65
	v_sub_f32_e32 v78, v66, v71
	v_sub_f32_e32 v86, v75, v72
	v_fma_f32 v72, v65, v76, -v70
	v_fmac_f32_e32 v72, v65, v78
	v_add_f32_e32 v66, v70, v72
	v_sub_f32_e32 v71, v67, v66
	v_mov_b32_e32 v73, v66
	v_pk_add_f32 v[66:67], v[66:67], v[70:71] neg_lo:[0,1] neg_hi:[0,1]
	v_cvt_f32_i32_e32 v64, v64
	v_pk_add_f32 v[66:67], v[66:67], v[72:73] neg_lo:[0,1] neg_hi:[0,1]
	v_rcp_f32_e32 v84, v83
	v_add_f32_e32 v67, v74, v67
	v_add_f32_e32 v66, v66, v67
	v_add_f32_e32 v67, v71, v66
	v_mul_f32_e32 v73, v77, v67
	v_mul_f32_e32 v70, v76, v73
	v_fma_f32 v72, v73, v76, -v70
	v_sub_f32_e32 v71, v71, v67
	v_fmac_f32_e32 v72, v73, v78
	v_add_f32_e32 v74, v66, v71
	v_add_f32_e32 v75, v65, v73
	v_add_f32_e32 v66, v70, v72
	v_sub_f32_e32 v65, v75, v65
	v_sub_f32_e32 v71, v67, v66
	v_sub_f32_e32 v65, v73, v65
	v_mov_b32_e32 v73, v66
	v_pk_add_f32 v[66:67], v[66:67], v[70:71] neg_lo:[0,1] neg_hi:[0,1]
	v_cmp_neq_f32_e32 vcc, s40, v68
	v_pk_add_f32 v[66:67], v[66:67], v[72:73] neg_lo:[0,1] neg_hi:[0,1]
	v_mul_f32_e32 v87, v69, v84
	v_add_f32_e32 v67, v74, v67
	v_add_f32_e32 v66, v66, v67
	v_add_f32_e32 v66, v71, v66
	v_mul_f32_e32 v66, v77, v66
	v_add_f32_e32 v65, v65, v66
	v_add_f32_e32 v66, v75, v65
	v_mul_f32_e32 v70, v66, v66
	v_sub_f32_e32 v71, v66, v75
	v_fmamk_f32 v72, v70, 0x3e9b6dac, v189
	v_sub_f32_e32 v71, v65, v71
	v_mul_f32_e32 v65, v66, v70
	v_fmaak_f32 v203, v70, v72, 0x3f2aaada
	v_ldexp_f32 v73, v71, 1
	v_pk_mul_f32 v[70:71], v[64:65], v[202:203]
	v_ldexp_f32 v67, v66, 1
	v_fma_f32 v66, v64, s39, -v70
	v_fmac_f32_e32 v66, 0xb102e308, v64
	v_pk_add_f32 v[64:65], v[70:71], v[66:67]
	v_mov_b32_e32 v72, v70
	v_sub_f32_e32 v76, v65, v67
	v_pk_add_f32 v[74:75], v[64:65], v[70:71] neg_lo:[0,1] neg_hi:[0,1]
	v_sub_f32_e32 v71, v71, v76
	v_add_f32_e32 v73, v73, v71
	v_pk_add_f32 v[78:79], v[64:65], v[72:73]
	v_mov_b32_e32 v67, v64
	v_mov_b32_e32 v75, v79
	v_pk_add_f32 v[80:81], v[66:67], v[74:75] neg_lo:[0,1] neg_hi:[0,1]
	v_pk_add_f32 v[66:67], v[66:67], v[74:75]
	v_mov_b32_e32 v70, v65
	v_mov_b32_e32 v77, v64
	v_pk_add_f32 v[64:65], v[66:67], v[64:65] op_sel:[1,0] op_sel_hi:[0,1] neg_lo:[0,1] neg_hi:[0,1]
	v_mov_b32_e32 v76, v73
	v_mov_b32_e32 v72, v79
	v_mov_b32_e32 v73, v67
	v_mov_b32_e32 v71, v64
	v_pk_add_f32 v[74:75], v[78:79], v[64:65] op_sel_hi:[1,0] neg_lo:[0,1] neg_hi:[0,1]
	v_pk_add_f32 v[64:65], v[72:73], v[70:71] neg_lo:[0,1] neg_hi:[0,1]
	v_mov_b32_e32 v74, v80
	v_pk_add_f32 v[64:65], v[76:77], v[64:65] neg_lo:[0,1] neg_hi:[0,1]
	v_mov_b32_e32 v81, v67
	v_pk_add_f32 v[70:71], v[74:75], v[64:65]
	v_cmp_lt_f32_e64 s[14:15], |v68|, s41
	v_pk_add_f32 v[72:73], v[70:71], v[70:71] op_sel:[0,1] op_sel_hi:[1,0]
	s_nop 0
	v_pk_add_f32 v[66:67], v[66:67], v[72:73] op_sel:[1,0] op_sel_hi:[0,1]
	v_mov_b32_e32 v71, v66
	v_mov_b32_e32 v65, v72
	v_pk_add_f32 v[72:73], v[70:71], v[80:81] neg_lo:[0,1] neg_hi:[0,1]
	s_nop 0
	v_sub_f32_e32 v67, v70, v72
	v_pk_add_f32 v[64:65], v[64:65], v[72:73] neg_lo:[0,1] neg_hi:[0,1]
	v_sub_f32_e32 v67, v80, v67
	v_add_f32_e32 v64, v64, v67
	v_add_f32_e32 v64, v64, v65
	v_add_f32_e32 v64, v66, v64
	v_cndmask_b32_e32 v64, v217, v64, vcc
	v_cmp_nlt_f32_e32 vcc, 1.0, v68
	s_nop 1
	v_cndmask_b32_e32 v64, v218, v64, vcc
	v_cmp_neq_f32_e32 vcc, 1.0, v68
	s_nop 1
	v_cndmask_b32_e32 v64, v219, v64, vcc
	v_cndmask_b32_e64 v99, v64, -v68, s[14:15]
	v_mul_f32_e32 v64, v83, v87
	v_fma_f32 v66, v87, v83, -v64
	v_fmac_f32_e32 v66, v87, v85
	v_add_f32_e32 v68, v64, v66
	v_sub_f32_e32 v65, v69, v68
	v_pk_add_f32 v[70:71], v[68:69], v[64:65] neg_lo:[0,1] neg_hi:[0,1]
	v_mov_b32_e32 v67, v68
	v_pk_add_f32 v[66:67], v[70:71], v[66:67] neg_lo:[0,1] neg_hi:[0,1]
	s_lshl_b64 s[14:15], s[16:17], 12
	v_add_f32_e32 v64, v86, v67
	v_add_f32_e32 v66, v66, v64
	v_add_f32_e32 v67, v65, v66
	v_mul_f32_e32 v72, v84, v67
	v_mul_f32_e32 v64, v83, v72
	v_fma_f32 v68, v72, v83, -v64
	v_fmac_f32_e32 v68, v72, v85
	v_sub_f32_e32 v65, v65, v67
	v_add_f32_e32 v73, v66, v65
	v_add_f32_e32 v66, v64, v68
	v_sub_f32_e32 v65, v67, v66
	v_pk_add_f32 v[70:71], v[66:67], v[64:65] neg_lo:[0,1] neg_hi:[0,1]
	v_mov_b32_e32 v69, v66
	v_pk_add_f32 v[66:67], v[70:71], v[68:69] neg_lo:[0,1] neg_hi:[0,1]
	s_or_b32 s14, s14, s46
	v_add_f32_e32 v64, v73, v67
	v_add_f32_e32 v64, v66, v64
	v_add_f32_e32 v64, v65, v64
	v_add_f32_e32 v65, v87, v72
	v_sub_f32_e32 v66, v65, v87
	v_mul_f32_e32 v64, v84, v64
	v_sub_f32_e32 v66, v72, v66
	v_add_f32_e32 v66, v66, v64
	v_add_f32_e32 v67, v65, v66
	v_mul_f32_e32 v68, v67, v67
	v_fmamk_f32 v64, v68, 0x3e9b6dac, v189
	v_fmaak_f32 v203, v68, v64, 0x3f2aaada
	v_cvt_f32_i32_e32 v64, v82
	v_sub_f32_e32 v65, v67, v65
	v_sub_f32_e32 v65, v66, v65
	v_ldexp_f32 v86, v65, 1
	v_mul_f32_e32 v65, v67, v68
	s_mul_i32 s17, s15, 0x1c00
	s_mul_hi_u32 s46, s14, 0x1c00
	v_pk_mul_f32 v[82:83], v[64:65], v[202:203]
	s_add_i32 s46, s46, s17
	s_mul_i32 s17, s14, 0x1c00
	v_fma_f32 v80, v64, s39, -v82
	s_add_u32 s17, s0, s17
	v_ldexp_f32 v81, v67, 1
	v_fmac_f32_e32 v80, 0xb102e308, v64
	s_addc_u32 s49, s1, s46
	s_lshl_b32 s46, s4, 7
	s_lshl_b32 s48, s4, 8
	v_pk_add_f32 v[84:85], v[82:83], v[80:81]
	s_add_u32 s48, s17, s48
	v_sub_f32_e32 v64, v85, v81
	s_addc_u32 s49, s49, 0
	v_sub_f32_e32 v81, v83, v64
	v_lshl_add_u64 v[64:65], s[48:49], 0, v[166:167]
	v_lshl_add_u64 v[72:73], v[64:65], 0, v[196:197]
	v_add_co_u32_e32 v74, vcc, s27, v72
	v_or_b32_e32 v87, s46, v162
	s_nop 0
	v_addc_co_u32_e32 v75, vcc, 0, v73, vcc
	v_add_co_u32_e32 v76, vcc, s29, v72
	v_lshl_add_u64 v[66:67], v[64:65], 0, v[194:195]
	s_nop 0
	v_addc_co_u32_e32 v77, vcc, 0, v73, vcc
	v_lshlrev_b32_e32 v87, 2, v87
	global_load_dwordx4 v[64:67], v[66:67], off offset:3072
	s_nop 0
	global_load_dwordx4 v[68:71], v[72:73], off offset:3072
	s_nop 0
	global_load_dwordx4 v[72:75], v[74:75], off offset:3072
	s_nop 0
	global_load_dwordx4 v[76:79], v[76:77], off offset:3072
	s_nop 0
	global_load_dword v228, v87, s[56:57]
	global_load_dword v227, v87, s[56:57] offset:64
	global_load_dword v226, v87, s[56:57] offset:128
	global_load_dword v225, v87, s[56:57] offset:192
	global_load_dword v224, v87, s[56:57] offset:256
	global_load_dword v223, v87, s[56:57] offset:320
	global_load_dword v222, v87, s[56:57] offset:384
	global_load_dword v203, v87, s[56:57] offset:448
	v_add_f32_e32 v87, v86, v81
	v_mov_b32_e32 v86, v82
	v_pk_add_f32 v[82:83], v[84:85], v[82:83] neg_lo:[0,1] neg_hi:[0,1]
	v_pk_add_f32 v[88:89], v[84:85], v[86:87]
	v_mov_b32_e32 v81, v84
	v_mov_b32_e32 v83, v89
	v_pk_add_f32 v[92:93], v[80:81], v[82:83] neg_lo:[0,1] neg_hi:[0,1]
	v_pk_add_f32 v[80:81], v[80:81], v[82:83]
	v_mov_b32_e32 v94, v85
	v_pk_add_f32 v[82:83], v[80:81], v[84:85] op_sel:[1,0] op_sel_hi:[0,1] neg_lo:[0,1] neg_hi:[0,1]
	v_pk_add_f32 v[90:91], v[88:89], v[82:83] op_sel_hi:[1,0] neg_lo:[0,1] neg_hi:[0,1]
	v_mov_b32_e32 v88, v89
	v_mov_b32_e32 v89, v81
	v_mov_b32_e32 v95, v82
	v_pk_add_f32 v[82:83], v[88:89], v[94:95] neg_lo:[0,1] neg_hi:[0,1]
	v_mov_b32_e32 v86, v87
	v_mov_b32_e32 v87, v84
	v_pk_add_f32 v[84:85], v[86:87], v[82:83] neg_lo:[0,1] neg_hi:[0,1]
	v_mov_b32_e32 v90, v92
	v_pk_add_f32 v[88:89], v[90:91], v[84:85]
	ds_write_b128 v191, v[0:3]
	ds_write_b128 v191, v[4:7] offset:38912
	v_pk_add_f32 v[86:87], v[88:89], v[88:89] op_sel:[0,1] op_sel_hi:[1,0]
	v_mov_b32_e32 v93, v81
	v_pk_add_f32 v[94:95], v[80:81], v[86:87] op_sel:[1,0] op_sel_hi:[0,1]
	v_add_u32_e32 v80, s42, v168
	ds_write_b128 v80, v[56:59]
	ds_write_b128 v191, v[8:11] offset:9728
	ds_write_b128 v191, v[12:15] offset:48640
	ds_write_b128 v80, v[16:19] offset:8192
	ds_write_b128 v191, v[20:23] offset:19456
	ds_write_b128 v191, v[24:27] offset:58368
	ds_write_b128 v80, v[28:31] offset:16384
	ds_write_b128 v191, v[32:35] offset:29184
	ds_write_b128 v193, v[36:39] offset:58368
	ds_write_b128 v80, v[40:43] offset:24576
	s_waitcnt lgkmcnt(0)
	s_barrier
	ds_read_b128 v[80:83], v204
	v_mov_b32_e32 v89, v94
	v_pk_add_f32 v[90:91], v[88:89], v[92:93] neg_lo:[0,1] neg_hi:[0,1]
	v_mov_b32_e32 v85, v86
	v_pk_add_f32 v[96:97], v[84:85], v[90:91] neg_lo:[0,1] neg_hi:[0,1]
	ds_read_b128 v[84:87], v204 offset:64
	s_waitcnt lgkmcnt(0)
	v_mfma_f32_16x16x32_bf16 v[80:83], v[44:47], v[80:83], 0
	v_sub_f32_e32 v93, v88, v90
	ds_read_b128 v[88:91], v204 offset:128
	v_cmp_neq_f32_e32 vcc, s40, v98
	v_mfma_f32_16x16x32_bf16 v[80:83], v[48:51], v[84:87], v[80:83]
	v_sub_f32_e32 v84, v92, v93
	v_add_f32_e32 v92, v96, v84
	ds_read_b128 v[84:87], v204 offset:192
	s_waitcnt lgkmcnt(1)
	v_mfma_f32_16x16x32_bf16 v[80:83], v[52:55], v[88:91], v[80:83]
	v_add_f32_e32 v88, v92, v97
	v_add_f32_e32 v92, v94, v88
	ds_read_b128 v[88:91], v204 offset:4864
	s_waitcnt lgkmcnt(1)
	v_mfma_f32_16x16x32_bf16 v[100:103], v[60:63], v[84:87], v[80:83]
	v_cndmask_b32_e32 v92, v217, v92, vcc
	v_cmp_nlt_f32_e32 vcc, 1.0, v98
	v_cmp_lt_f32_e64 s[48:49], |v98|, s41
	ds_read_b128 v[80:83], v204 offset:4928
	s_waitcnt lgkmcnt(1)
	v_mfma_f32_16x16x32_bf16 v[84:87], v[44:47], v[88:91], 0
	ds_read_b128 v[88:91], v204 offset:4992
	v_cndmask_b32_e32 v92, v218, v92, vcc
	v_cmp_neq_f32_e32 vcc, 1.0, v98
	s_waitcnt lgkmcnt(1)
	v_mfma_f32_16x16x32_bf16 v[80:83], v[48:51], v[80:83], v[84:87]
	v_mul_f32_e32 v230, 0x3fb8aa3b, v99
	v_cndmask_b32_e32 v92, v219, v92, vcc
	v_cndmask_b32_e64 v120, v92, -v98, s[48:49]
	ds_read_b128 v[84:87], v204 offset:5056
	s_waitcnt lgkmcnt(1)
	v_mfma_f32_16x16x32_bf16 v[80:83], v[52:55], v[88:91], v[80:83]
	s_lshl_b32 s16, s16, 2
	s_waitcnt lgkmcnt(0)
	v_mfma_f32_16x16x32_bf16 v[104:107], v[60:63], v[84:87], v[80:83]
	s_nop 4
	ds_read_b128 v[80:83], v204 offset:9728
	ds_read_b128 v[84:87], v204 offset:9792
	s_waitcnt lgkmcnt(1)
	v_mfma_f32_16x16x32_bf16 v[80:83], v[44:47], v[80:83], 0
	s_waitcnt lgkmcnt(0)
	v_mfma_f32_16x16x32_bf16 v[80:83], v[48:51], v[84:87], v[80:83]
	ds_read_b128 v[84:87], v204 offset:9856
	ds_read_b128 v[88:91], v204 offset:9920
	s_waitcnt lgkmcnt(1)
	v_mfma_f32_16x16x32_bf16 v[80:83], v[52:55], v[84:87], v[80:83]
	s_waitcnt lgkmcnt(0)
	v_mfma_f32_16x16x32_bf16 v[108:111], v[60:63], v[88:91], v[80:83]
	s_nop 5
	ds_read_b128 v[80:83], v204 offset:14592
	ds_read_b128 v[84:87], v204 offset:14656
	s_waitcnt lgkmcnt(1)
	v_mfma_f32_16x16x32_bf16 v[80:83], v[44:47], v[80:83], 0
	s_waitcnt lgkmcnt(0)
	v_mfma_f32_16x16x32_bf16 v[80:83], v[48:51], v[84:87], v[80:83]
	ds_read_b128 v[84:87], v204 offset:14720
	ds_read_b128 v[88:91], v204 offset:14784
	s_waitcnt lgkmcnt(1)
	v_mfma_f32_16x16x32_bf16 v[80:83], v[52:55], v[84:87], v[80:83]
	s_waitcnt lgkmcnt(0)
	v_mfma_f32_16x16x32_bf16 v[96:99], v[60:63], v[88:91], v[80:83]
	s_nop 5
	ds_read_b128 v[80:83], v204 offset:19456
	ds_read_b128 v[84:87], v204 offset:19520
	s_waitcnt lgkmcnt(1)
	v_mfma_f32_16x16x32_bf16 v[80:83], v[44:47], v[80:83], 0
	s_waitcnt lgkmcnt(0)
	v_mfma_f32_16x16x32_bf16 v[80:83], v[48:51], v[84:87], v[80:83]
	ds_read_b128 v[84:87], v204 offset:19584
	ds_read_b128 v[88:91], v204 offset:19648
	s_waitcnt lgkmcnt(1)
	v_mfma_f32_16x16x32_bf16 v[80:83], v[52:55], v[84:87], v[80:83]
	s_waitcnt lgkmcnt(0)
	v_mfma_f32_16x16x32_bf16 v[92:95], v[60:63], v[88:91], v[80:83]
	s_nop 5
	ds_read_b128 v[80:83], v204 offset:24320
	ds_read_b128 v[84:87], v204 offset:24384
	s_waitcnt lgkmcnt(1)
	v_mfma_f32_16x16x32_bf16 v[80:83], v[44:47], v[80:83], 0
	s_waitcnt lgkmcnt(0)
	v_mfma_f32_16x16x32_bf16 v[80:83], v[48:51], v[84:87], v[80:83]
	ds_read_b128 v[84:87], v204 offset:24448
	ds_read_b128 v[88:91], v204 offset:24512
	s_waitcnt lgkmcnt(1)
	v_mfma_f32_16x16x32_bf16 v[80:83], v[52:55], v[84:87], v[80:83]
	s_waitcnt lgkmcnt(0)
	v_mfma_f32_16x16x32_bf16 v[88:91], v[60:63], v[88:91], v[80:83]
	s_nop 5
	ds_read_b128 v[80:83], v204 offset:29184
	ds_read_b128 v[84:87], v204 offset:29248
	s_waitcnt lgkmcnt(1)
	v_mfma_f32_16x16x32_bf16 v[80:83], v[44:47], v[80:83], 0
	s_waitcnt lgkmcnt(0)
	v_mfma_f32_16x16x32_bf16 v[80:83], v[48:51], v[84:87], v[80:83]
	ds_read_b128 v[84:87], v204 offset:29312
	ds_read_b128 v[112:115], v204 offset:29376
	s_waitcnt lgkmcnt(1)
	v_mfma_f32_16x16x32_bf16 v[80:83], v[52:55], v[84:87], v[80:83]
	s_waitcnt lgkmcnt(0)
	v_mfma_f32_16x16x32_bf16 v[84:87], v[60:63], v[112:115], v[80:83]
	s_nop 5
	ds_read_b128 v[80:83], v204 offset:34048
	ds_read_b128 v[112:115], v204 offset:34112
	s_waitcnt lgkmcnt(1)
	v_mfma_f32_16x16x32_bf16 v[80:83], v[44:47], v[80:83], 0
	s_waitcnt lgkmcnt(0)
	v_mfma_f32_16x16x32_bf16 v[80:83], v[48:51], v[112:115], v[80:83]
	ds_read_b128 v[112:115], v204 offset:34176
	ds_read_b128 v[116:119], v204 offset:34240
	s_waitcnt lgkmcnt(1)
	v_mfma_f32_16x16x32_bf16 v[80:83], v[52:55], v[112:115], v[80:83]
	s_waitcnt lgkmcnt(0)
	v_mfma_f32_16x16x32_bf16 v[80:83], v[60:63], v[116:119], v[80:83]
	v_add_u32_e32 v232, 1, v229
	v_sub_u32_e32 v114, v232, v162
	v_sub_u32_e32 v112, v229, v162
	v_cvt_f32_i32_e32 v115, v114
	v_mul_f32_e32 v231, 0x3fb8aa3b, v120
	v_cmp_lt_i32_e32 vcc, 0, v112
	v_cvt_f32_i32_e32 v112, v112
	v_add_u32_e32 v233, 3, v229
	v_cndmask_b32_e64 v113, -v231, v230, vcc
	v_cmp_lt_i32_e32 vcc, 0, v114
	v_mul_f32_e32 v112, v113, v112
	v_exp_f32_e32 v112, v112
	v_cndmask_b32_e64 v114, -v231, v230, vcc
	v_mul_f32_e32 v114, v114, v115
	v_exp_f32_e32 v114, v114
	v_cmp_ne_u32_e32 vcc, v232, v161
	v_add_u32_e32 v234, 2, v229
	s_or_b32 s4, s16, s4
	v_cndmask_b32_e32 v113, 2.0, v114, vcc
	v_cmp_ne_u32_e32 vcc, v229, v162
	v_sub_u32_e32 v114, v233, v162
	v_cvt_f32_i32_e32 v115, v114
	v_cndmask_b32_e32 v112, 2.0, v112, vcc
	v_pk_mul_f32 v[100:101], v[100:101], v[112:113]
	v_sub_u32_e32 v112, v234, v162
	v_cmp_lt_i32_e32 vcc, 0, v112
	v_cvt_f32_i32_e32 v112, v112
	v_cvt_pk_bf16_f32 v100, v100, v101
	v_cndmask_b32_e64 v113, -v231, v230, vcc
	v_cmp_lt_i32_e32 vcc, 0, v114
	v_mul_f32_e32 v112, v113, v112
	v_exp_f32_e32 v112, v112
	v_cndmask_b32_e64 v114, -v231, v230, vcc
	v_mul_f32_e32 v114, v114, v115
	v_exp_f32_e32 v114, v114
	v_cmp_ne_u32_e32 vcc, v233, v161
	s_add_i32 s16, s4, 32
	s_ashr_i32 s17, s16, 31
	v_cndmask_b32_e32 v113, 2.0, v114, vcc
	v_cmp_ne_u32_e32 vcc, v234, v162
	s_lshl_b64 s[16:17], s[16:17], 20
	s_add_u32 s4, s11, s16
	v_cndmask_b32_e32 v112, 2.0, v112, vcc
	v_pk_mul_f32 v[102:103], v[102:103], v[112:113]
	v_sub_u32_e32 v112, v232, v180
	v_cvt_pk_bf16_f32 v101, v102, v103
	v_sub_u32_e32 v102, v229, v180
	v_cvt_f32_i32_e32 v113, v112
	v_cmp_lt_i32_e32 vcc, 0, v102
	v_cvt_f32_i32_e32 v102, v102
	s_addc_u32 s17, s13, s17
	v_cndmask_b32_e64 v103, -v231, v230, vcc
	v_cmp_lt_i32_e32 vcc, 0, v112
	v_mul_f32_e32 v102, v103, v102
	v_exp_f32_e32 v102, v102
	v_cndmask_b32_e64 v112, -v231, v230, vcc
	v_mul_f32_e32 v112, v112, v113
	v_exp_f32_e32 v112, v112
	v_cmp_ne_u32_e32 vcc, v232, v163
	s_lshl_b32 s16, s47, 15
	s_add_u32 s16, s4, s16
	v_cndmask_b32_e32 v103, 2.0, v112, vcc
	v_cmp_ne_u32_e32 vcc, v229, v180
	v_sub_u32_e32 v112, v233, v180
	v_cvt_f32_i32_e32 v113, v112
	v_cndmask_b32_e32 v102, 2.0, v102, vcc
	v_pk_mul_f32 v[102:103], v[104:105], v[102:103]
	v_sub_u32_e32 v104, v234, v180
	v_cmp_lt_i32_e32 vcc, 0, v104
	v_cvt_f32_i32_e32 v104, v104
	v_cvt_pk_bf16_f32 v102, v102, v103
	v_cndmask_b32_e64 v105, -v231, v230, vcc
	v_cmp_lt_i32_e32 vcc, 0, v112
	v_mul_f32_e32 v104, v105, v104
	v_exp_f32_e32 v104, v104
	v_cndmask_b32_e64 v112, -v231, v230, vcc
	v_mul_f32_e32 v112, v112, v113
	v_exp_f32_e32 v112, v112
	v_cmp_ne_u32_e32 vcc, v233, v163
	s_addc_u32 s17, s17, 0
	global_load_dwordx4 v[0:3], v198, s[16:17]
	global_load_dwordx4 v[4:7], v206, s[16:17]
	global_load_dwordx4 v[8:11], v208, s[16:17]
	global_load_dwordx4 v[12:15], v210, s[16:17]
	s_nop 0
	v_cndmask_b32_e32 v105, 2.0, v112, vcc
	v_cmp_ne_u32_e32 vcc, v234, v180
	s_nop 1
	v_cndmask_b32_e32 v104, 2.0, v104, vcc
	v_pk_mul_f32 v[104:105], v[106:107], v[104:105]
	s_nop 0
	v_cvt_pk_bf16_f32 v103, v104, v105
	ds_write2_b64 v205, v[100:101], v[102:103] offset1:80
	v_sub_u32_e32 v102, v232, v182
	v_sub_u32_e32 v100, v229, v182
	v_cvt_f32_i32_e32 v103, v102
	v_cmp_lt_i32_e32 vcc, 0, v100
	v_cvt_f32_i32_e32 v100, v100
	v_sub_u32_e32 v104, v233, v182
	v_cndmask_b32_e64 v101, -v231, v230, vcc
	v_cmp_lt_i32_e32 vcc, 0, v102
	v_mul_f32_e32 v100, v101, v100
	v_exp_f32_e32 v100, v100
	v_cndmask_b32_e64 v102, -v231, v230, vcc
	v_mul_f32_e32 v102, v102, v103
	v_exp_f32_e32 v102, v102
	v_cmp_ne_u32_e32 vcc, v232, v165
	v_cvt_f32_i32_e32 v105, v104
	s_nop 0
	v_cndmask_b32_e32 v101, 2.0, v102, vcc
	v_cmp_ne_u32_e32 vcc, v229, v182
	v_sub_u32_e32 v102, v234, v182
	s_nop 0
	v_cndmask_b32_e32 v100, 2.0, v100, vcc
	v_cmp_lt_i32_e32 vcc, 0, v102
	v_cvt_f32_i32_e32 v102, v102
	v_pk_mul_f32 v[100:101], v[108:109], v[100:101]
	v_cndmask_b32_e64 v103, -v231, v230, vcc
	v_cmp_lt_i32_e32 vcc, 0, v104
	v_mul_f32_e32 v102, v103, v102
	v_exp_f32_e32 v102, v102
	v_cndmask_b32_e64 v104, -v231, v230, vcc
	v_mul_f32_e32 v104, v104, v105
	v_exp_f32_e32 v104, v104
	v_cmp_ne_u32_e32 vcc, v233, v165
	v_cvt_pk_bf16_f32 v100, v100, v101
	s_nop 0
	v_cndmask_b32_e32 v103, 2.0, v104, vcc
	v_cmp_ne_u32_e32 vcc, v234, v182
	v_sub_u32_e32 v104, v232, v184
	v_cvt_f32_i32_e32 v105, v104
	v_cndmask_b32_e32 v102, 2.0, v102, vcc
	v_pk_mul_f32 v[102:103], v[110:111], v[102:103]
	s_nop 0
	v_cvt_pk_bf16_f32 v101, v102, v103
	v_sub_u32_e32 v102, v229, v184
	v_cmp_lt_i32_e32 vcc, 0, v102
	v_cvt_f32_i32_e32 v102, v102
	s_nop 0
	v_cndmask_b32_e64 v103, -v231, v230, vcc
	v_cmp_lt_i32_e32 vcc, 0, v104
	v_mul_f32_e32 v102, v103, v102
	v_exp_f32_e32 v102, v102
	v_cndmask_b32_e64 v104, -v231, v230, vcc
	v_mul_f32_e32 v104, v104, v105
	v_exp_f32_e32 v104, v104
	v_cmp_ne_u32_e32 vcc, v232, v169
	s_nop 1
	v_cndmask_b32_e32 v103, 2.0, v104, vcc
	v_cmp_ne_u32_e32 vcc, v229, v184
	v_sub_u32_e32 v104, v233, v184
	v_cvt_f32_i32_e32 v105, v104
	v_cndmask_b32_e32 v102, 2.0, v102, vcc
	v_pk_mul_f32 v[96:97], v[96:97], v[102:103]
	v_sub_u32_e32 v102, v234, v184
	v_cmp_lt_i32_e32 vcc, 0, v102
	v_cvt_f32_i32_e32 v102, v102
	v_cvt_pk_bf16_f32 v96, v96, v97
	v_cndmask_b32_e64 v103, -v231, v230, vcc
	v_cmp_lt_i32_e32 vcc, 0, v104
	v_mul_f32_e32 v102, v103, v102
	v_exp_f32_e32 v102, v102
	v_cndmask_b32_e64 v104, -v231, v230, vcc
	v_mul_f32_e32 v104, v104, v105
	v_exp_f32_e32 v104, v104
	v_cmp_ne_u32_e32 vcc, v233, v169
	s_nop 1
	v_cndmask_b32_e32 v103, 2.0, v104, vcc
	v_cmp_ne_u32_e32 vcc, v234, v184
	s_nop 1
	v_cndmask_b32_e32 v102, 2.0, v102, vcc
	v_pk_mul_f32 v[98:99], v[98:99], v[102:103]
	s_nop 0
	v_cvt_pk_bf16_f32 v97, v98, v99
	v_sub_u32_e32 v98, v232, v186
	ds_write2_b64 v205, v[100:101], v[96:97] offset0:160 offset1:240
	v_sub_u32_e32 v96, v229, v186
	v_cvt_f32_i32_e32 v99, v98
	v_cmp_lt_i32_e32 vcc, 0, v96
	v_cvt_f32_i32_e32 v96, v96
	s_nop 0
	v_cndmask_b32_e64 v97, -v231, v230, vcc
	v_cmp_lt_i32_e32 vcc, 0, v98
	v_mul_f32_e32 v96, v97, v96
	v_exp_f32_e32 v96, v96
	v_cndmask_b32_e64 v98, -v231, v230, vcc
	v_mul_f32_e32 v98, v98, v99
	v_exp_f32_e32 v98, v98
	v_cmp_ne_u32_e32 vcc, v232, v175
	s_nop 1
	v_cndmask_b32_e32 v97, 2.0, v98, vcc
	v_cmp_ne_u32_e32 vcc, v229, v186
	v_sub_u32_e32 v98, v233, v186
	v_cvt_f32_i32_e32 v99, v98
	v_cndmask_b32_e32 v96, 2.0, v96, vcc
	v_pk_mul_f32 v[92:93], v[96:97], v[92:93]
	v_sub_u32_e32 v96, v234, v186
	v_cmp_lt_i32_e32 vcc, 0, v96
	v_cvt_f32_i32_e32 v96, v96
	v_cvt_pk_bf16_f32 v92, v92, v93
	v_cndmask_b32_e64 v97, -v231, v230, vcc
	v_cmp_lt_i32_e32 vcc, 0, v98
	v_mul_f32_e32 v96, v97, v96
	v_exp_f32_e32 v96, v96
	v_cndmask_b32_e64 v98, -v231, v230, vcc
	v_mul_f32_e32 v98, v98, v99
	v_exp_f32_e32 v98, v98
	v_cmp_ne_u32_e32 vcc, v233, v175
	s_nop 1
	v_cndmask_b32_e32 v97, 2.0, v98, vcc
	v_cmp_ne_u32_e32 vcc, v234, v186
	s_nop 1
	v_cndmask_b32_e32 v96, 2.0, v96, vcc
	v_pk_mul_f32 v[94:95], v[96:97], v[94:95]
	v_sub_u32_e32 v96, v232, v188
	v_cvt_pk_bf16_f32 v93, v94, v95
	v_sub_u32_e32 v94, v229, v188
	v_cvt_f32_i32_e32 v97, v96
	v_cmp_lt_i32_e32 vcc, 0, v94
	v_cvt_f32_i32_e32 v94, v94
	s_nop 0
	v_cndmask_b32_e64 v95, -v231, v230, vcc
	v_cmp_lt_i32_e32 vcc, 0, v96
	v_mul_f32_e32 v94, v95, v94
	v_exp_f32_e32 v94, v94
	v_cndmask_b32_e64 v96, -v231, v230, vcc
	v_mul_f32_e32 v96, v96, v97
	v_exp_f32_e32 v96, v96
	v_cmp_ne_u32_e32 vcc, v232, v177
	s_nop 1
	v_cndmask_b32_e32 v95, 2.0, v96, vcc
	v_cmp_ne_u32_e32 vcc, v229, v188
	v_sub_u32_e32 v96, v233, v188
	v_cvt_f32_i32_e32 v97, v96
	v_cndmask_b32_e32 v94, 2.0, v94, vcc
	v_pk_mul_f32 v[88:89], v[94:95], v[88:89]
	v_sub_u32_e32 v94, v234, v188
	v_cmp_lt_i32_e32 vcc, 0, v94
	v_cvt_f32_i32_e32 v94, v94
	v_cvt_pk_bf16_f32 v88, v88, v89
	v_cndmask_b32_e64 v95, -v231, v230, vcc
	v_cmp_lt_i32_e32 vcc, 0, v96
	v_mul_f32_e32 v94, v95, v94
	v_exp_f32_e32 v94, v94
	v_cndmask_b32_e64 v96, -v231, v230, vcc
	v_mul_f32_e32 v96, v96, v97
	v_exp_f32_e32 v96, v96
	v_cmp_ne_u32_e32 vcc, v233, v177
	s_nop 1
	v_cndmask_b32_e32 v95, 2.0, v96, vcc
	v_cmp_ne_u32_e32 vcc, v234, v188
	v_add_u32_e32 v96, 0, v168
	s_nop 0
	v_cndmask_b32_e32 v94, 2.0, v94, vcc
	v_pk_mul_f32 v[90:91], v[94:95], v[90:91]
	s_nop 0
	v_cvt_pk_bf16_f32 v89, v90, v91
	v_add_u32_e32 v90, 0x800, v205
	ds_write2_b64 v90, v[92:93], v[88:89] offset0:64 offset1:144
	v_sub_u32_e32 v90, v232, v190
	v_sub_u32_e32 v88, v229, v190
	v_cvt_f32_i32_e32 v91, v90
	v_cmp_lt_i32_e32 vcc, 0, v88
	v_cvt_f32_i32_e32 v88, v88
	s_nop 0
	v_cndmask_b32_e64 v89, -v231, v230, vcc
	v_cmp_lt_i32_e32 vcc, 0, v90
	v_mul_f32_e32 v88, v89, v88
	v_exp_f32_e32 v88, v88
	v_cndmask_b32_e64 v90, -v231, v230, vcc
	v_mul_f32_e32 v90, v90, v91
	v_exp_f32_e32 v90, v90
	v_cmp_ne_u32_e32 vcc, v232, v181
	s_nop 1
	v_cndmask_b32_e32 v89, 2.0, v90, vcc
	v_cmp_ne_u32_e32 vcc, v229, v190
	v_sub_u32_e32 v90, v233, v190
	v_cvt_f32_i32_e32 v91, v90
	v_cndmask_b32_e32 v88, 2.0, v88, vcc
	v_pk_mul_f32 v[84:85], v[88:89], v[84:85]
	v_sub_u32_e32 v88, v234, v190
	v_cmp_lt_i32_e32 vcc, 0, v88
	v_cvt_f32_i32_e32 v88, v88
	v_cvt_pk_bf16_f32 v84, v84, v85
	v_cndmask_b32_e64 v89, -v231, v230, vcc
	v_cmp_lt_i32_e32 vcc, 0, v90
	v_mul_f32_e32 v88, v89, v88
	v_exp_f32_e32 v88, v88
	v_cndmask_b32_e64 v90, -v231, v230, vcc
	v_mul_f32_e32 v90, v90, v91
	v_exp_f32_e32 v90, v90
	v_cmp_ne_u32_e32 vcc, v233, v181
	s_nop 1
	v_cndmask_b32_e32 v89, 2.0, v90, vcc
	v_cmp_ne_u32_e32 vcc, v234, v190
	s_nop 1
	v_cndmask_b32_e32 v88, 2.0, v88, vcc
	v_pk_mul_f32 v[86:87], v[88:89], v[86:87]
	v_sub_u32_e32 v88, v232, v192
	v_cvt_pk_bf16_f32 v85, v86, v87
	v_sub_u32_e32 v86, v229, v192
	v_cvt_f32_i32_e32 v89, v88
	v_cmp_lt_i32_e32 vcc, 0, v86
	v_cvt_f32_i32_e32 v86, v86
	s_nop 0
	v_cndmask_b32_e64 v87, -v231, v230, vcc
	v_cmp_lt_i32_e32 vcc, 0, v88
	v_mul_f32_e32 v86, v87, v86
	v_exp_f32_e32 v86, v86
	v_cndmask_b32_e64 v88, -v231, v230, vcc
	v_mul_f32_e32 v88, v88, v89
	v_exp_f32_e32 v88, v88
	v_cmp_ne_u32_e32 vcc, v232, v183
	s_nop 1
	v_cndmask_b32_e32 v87, 2.0, v88, vcc
	v_cmp_ne_u32_e32 vcc, v229, v192
	v_sub_u32_e32 v88, v233, v192
	v_cvt_f32_i32_e32 v89, v88
	v_cndmask_b32_e32 v86, 2.0, v86, vcc
	v_pk_mul_f32 v[80:81], v[86:87], v[80:81]
	v_sub_u32_e32 v86, v234, v192
	v_cmp_lt_i32_e32 vcc, 0, v86
	v_cvt_f32_i32_e32 v86, v86
	v_cvt_pk_bf16_f32 v80, v80, v81
	v_cndmask_b32_e64 v87, -v231, v230, vcc
	v_cmp_lt_i32_e32 vcc, 0, v88
	v_mul_f32_e32 v86, v87, v86
	v_exp_f32_e32 v86, v86
	v_cndmask_b32_e64 v88, -v231, v230, vcc
	v_mul_f32_e32 v88, v88, v89
	v_exp_f32_e32 v88, v88
	v_cmp_ne_u32_e32 vcc, v233, v183
	s_nop 1
	v_cndmask_b32_e32 v87, 2.0, v88, vcc
	v_cmp_ne_u32_e32 vcc, v234, v192
	s_nop 1
	v_cndmask_b32_e32 v86, 2.0, v86, vcc
	v_pk_mul_f32 v[82:83], v[86:87], v[82:83]
	s_nop 0
	v_cvt_pk_bf16_f32 v81, v82, v83
	v_add_u32_e32 v82, 0xc00, v205
	ds_write2_b64 v82, v[84:85], v[80:81] offset0:96 offset1:176
	s_waitcnt lgkmcnt(0)
	s_barrier
	s_waitcnt vmcnt(0)
	ds_write_b128 v96, v[0:3]
	ds_write_b128 v207, v[4:7]
	ds_write_b128 v209, v[8:11]
	ds_write_b128 v211, v[12:15]
	ds_read_b64_tr_b16 v[80:81], v212
	ds_read_b64_tr_b16 v[82:83], v212 offset:160
	ds_read_b64_tr_b16 v[86:87], v213 offset:40128
	ds_read_b64_tr_b16 v[84:85], v213 offset:38912
	ds_read_b64_tr_b16 v[88:89], v213 offset:38944
	ds_read_b64_tr_b16 v[90:91], v213 offset:40160
	ds_read_b64_tr_b16 v[92:93], v213 offset:39136
	ds_read_b64_tr_b16 v[96:97], v213 offset:40192
	ds_read_b64_tr_b16 v[94:95], v213 offset:38976
	ds_read_b64_tr_b16 v[98:99], v213 offset:39008
	ds_read_b64_tr_b16 v[102:103], v213 offset:39040
	ds_read_b64_tr_b16 v[106:107], v213 offset:39072
	ds_read_b64_tr_b16 v[100:101], v213 offset:40224
	ds_read_b64_tr_b16 v[104:105], v213 offset:40256
	ds_read_b64_tr_b16 v[108:109], v213 offset:40288
	s_waitcnt lgkmcnt(6)
	v_mfma_f32_16x16x32_bf16 v[110:113], v[80:83], v[94:97], 0
	s_waitcnt lgkmcnt(2)
	v_mfma_f32_16x16x32_bf16 v[96:99], v[80:83], v[98:101], 0
	s_waitcnt lgkmcnt(1)
	v_mfma_f32_16x16x32_bf16 v[100:103], v[80:83], v[102:105], 0
	ds_read_b64_tr_b16 v[104:105], v213 offset:39104
	s_waitcnt lgkmcnt(1)
	v_mfma_f32_16x16x32_bf16 v[114:117], v[80:83], v[106:109], 0
	ds_read_b64_tr_b16 v[106:107], v213 offset:40320
	ds_read_b64_tr_b16 v[94:95], v213 offset:40352
	v_mfma_f32_16x16x32_bf16 v[84:87], v[80:83], v[84:87], 0
	v_mfma_f32_16x16x32_bf16 v[88:91], v[80:83], v[88:91], 0
	s_waitcnt lgkmcnt(1)
	v_mfma_f32_16x16x32_bf16 v[104:107], v[80:83], v[104:107], 0
	s_waitcnt lgkmcnt(0)
	v_mfma_f32_16x16x32_bf16 v[80:83], v[80:83], v[92:95], 0
	ds_read_b64_tr_b16 v[92:93], v212 offset:1280
	ds_read_b64_tr_b16 v[94:95], v212 offset:1440
	ds_read_b64_tr_b16 v[120:121], v213 offset:49856
	ds_read_b64_tr_b16 v[118:119], v213 offset:48640
	ds_read_b64_tr_b16 v[122:123], v213 offset:48672
	ds_read_b64_tr_b16 v[124:125], v213 offset:49888
	ds_read_b64_tr_b16 v[108:109], v213 offset:48864
	s_waitcnt lgkmcnt(3)
	v_mfma_f32_16x16x32_bf16 v[84:87], v[92:95], v[118:121], v[84:87]
	ds_read_b64_tr_b16 v[120:121], v213 offset:49920
	s_waitcnt lgkmcnt(2)
	v_mfma_f32_16x16x32_bf16 v[88:91], v[92:95], v[122:125], v[88:91]
	ds_read_b64_tr_b16 v[118:119], v213 offset:48704
	ds_read_b64_tr_b16 v[122:123], v213 offset:48736
	ds_read_b64_tr_b16 v[126:127], v213 offset:48768
	ds_read_b64_tr_b16 v[130:131], v213 offset:48800
	ds_read_b64_tr_b16 v[124:125], v213 offset:49952
	ds_read_b64_tr_b16 v[128:129], v213 offset:49984
	ds_read_b64_tr_b16 v[132:133], v213 offset:50016
	s_waitcnt lgkmcnt(6)
	v_mfma_f32_16x16x32_bf16 v[118:121], v[92:95], v[118:121], v[110:113]
	s_waitcnt lgkmcnt(2)
	v_mfma_f32_16x16x32_bf16 v[96:99], v[92:95], v[122:125], v[96:99]
	s_nop 0
	ds_read_b64_tr_b16 v[112:113], v213 offset:48832
	s_waitcnt lgkmcnt(1)
	v_mfma_f32_16x16x32_bf16 v[122:125], v[92:95], v[130:133], v[114:117]
	s_nop 2
	ds_read_b64_tr_b16 v[114:115], v213 offset:50048
	ds_read_b64_tr_b16 v[110:111], v213 offset:50080
	v_mfma_f32_16x16x32_bf16 v[100:103], v[92:95], v[126:129], v[100:103]
	s_waitcnt lgkmcnt(1)
	v_mfma_f32_16x16x32_bf16 v[104:107], v[92:95], v[112:115], v[104:107]
	s_waitcnt lgkmcnt(0)
	v_mfma_f32_16x16x32_bf16 v[80:83], v[92:95], v[108:111], v[80:83]
	ds_read_b64_tr_b16 v[92:93], v212 offset:2560
	ds_read_b64_tr_b16 v[94:95], v212 offset:2720
	ds_read_b64_tr_b16 v[110:111], v213 offset:59584
	ds_read_b64_tr_b16 v[108:109], v213 offset:58368
	ds_read_b64_tr_b16 v[112:113], v213 offset:58400
	ds_read_b64_tr_b16 v[114:115], v213 offset:59616
	ds_read_b64_tr_b16 v[116:117], v213 offset:58592
	s_waitcnt lgkmcnt(3)
	v_mfma_f32_16x16x32_bf16 v[84:87], v[92:95], v[108:111], v[84:87]
	ds_read_b64_tr_b16 v[110:111], v213 offset:59648
	s_waitcnt lgkmcnt(2)
	v_mfma_f32_16x16x32_bf16 v[88:91], v[92:95], v[112:115], v[88:91]
	ds_read_b64_tr_b16 v[108:109], v213 offset:58432
	ds_read_b64_tr_b16 v[112:113], v213 offset:58464
	ds_read_b64_tr_b16 v[126:127], v213 offset:58496
	ds_read_b64_tr_b16 v[130:131], v213 offset:58528
	ds_read_b64_tr_b16 v[114:115], v213 offset:59680
	ds_read_b64_tr_b16 v[128:129], v213 offset:59712
	ds_read_b64_tr_b16 v[132:133], v213 offset:59744
	s_waitcnt lgkmcnt(6)
	v_mfma_f32_16x16x32_bf16 v[134:137], v[92:95], v[108:111], v[118:121]
	s_waitcnt lgkmcnt(2)
	v_mfma_f32_16x16x32_bf16 v[112:115], v[92:95], v[112:115], v[96:99]
	s_nop 2
	ds_read_b64_tr_b16 v[96:97], v213 offset:58560
	ds_read_b64_tr_b16 v[98:99], v213 offset:59776
	ds_read_b64_tr_b16 v[118:119], v213 offset:59808
	s_waitcnt lgkmcnt(4)
	v_mfma_f32_16x16x32_bf16 v[126:129], v[92:95], v[126:129], v[100:103]
	s_waitcnt lgkmcnt(3)
	v_mfma_f32_16x16x32_bf16 v[120:123], v[92:95], v[130:133], v[122:125]
	s_waitcnt lgkmcnt(1)
	v_mfma_f32_16x16x32_bf16 v[130:133], v[92:95], v[96:99], v[104:107]
	s_waitcnt lgkmcnt(0)
	v_mfma_f32_16x16x32_bf16 v[116:119], v[92:95], v[116:119], v[80:83]
	ds_read_b64_tr_b16 v[138:139], v212 offset:3840
	ds_read_b64_tr_b16 v[140:141], v212 offset:4000
	s_nop 0
	ds_read_b64_tr_b16 v[82:83], v214 offset:59584
	ds_read_b64_tr_b16 v[80:81], v214 offset:58368
	ds_read_b64_tr_b16 v[92:93], v214 offset:58400
	ds_read_b64_tr_b16 v[94:95], v214 offset:59616
	ds_read_b64_tr_b16 v[124:125], v214 offset:58592
	s_waitcnt lgkmcnt(3)
	v_mfma_f32_16x16x32_bf16 v[108:111], v[138:141], v[80:83], v[84:87]
	ds_read_b64_tr_b16 v[82:83], v214 offset:59648
	s_waitcnt lgkmcnt(2)
	v_mfma_f32_16x16x32_bf16 v[104:107], v[138:141], v[92:95], v[88:91]
	ds_read_b64_tr_b16 v[80:81], v214 offset:58432
	ds_read_b64_tr_b16 v[84:85], v214 offset:58464
	s_nop 0
	ds_read_b64_tr_b16 v[88:89], v214 offset:58496
	ds_read_b64_tr_b16 v[92:93], v214 offset:58528
	ds_read_b64_tr_b16 v[86:87], v214 offset:59680
	ds_read_b64_tr_b16 v[90:91], v214 offset:59712
	ds_read_b64_tr_b16 v[94:95], v214 offset:59744
	s_waitcnt lgkmcnt(6)
	v_mfma_f32_16x16x32_bf16 v[96:99], v[138:141], v[80:83], v[134:137]
	ds_read_b64_tr_b16 v[80:81], v214 offset:58560
	s_waitcnt lgkmcnt(2)
	v_mfma_f32_16x16x32_bf16 v[88:91], v[138:141], v[88:91], v[126:129]
	ds_read_b64_tr_b16 v[82:83], v214 offset:59776
	s_nop 1
	ds_read_b64_tr_b16 v[126:127], v214 offset:59808
	v_mfma_f32_16x16x32_bf16 v[100:103], v[138:141], v[84:87], v[112:115]
	s_waitcnt lgkmcnt(3)
	v_mfma_f32_16x16x32_bf16 v[92:95], v[138:141], v[92:95], v[120:123]
	s_waitcnt lgkmcnt(1)
	v_mfma_f32_16x16x32_bf16 v[80:83], v[138:141], v[80:83], v[130:133]
	s_waitcnt lgkmcnt(0)
	v_mfma_f32_16x16x32_bf16 v[84:87], v[138:141], v[124:127], v[116:119]
	v_add_u32_e32 v112, s42, v187
	ds_read_b128 v[112:115], v112
	v_add_u32_e32 v199, 0, v187
	v_add_u32_e32 v116, 0x13400, v199
	ds_read_b128 v[116:119], v116
	v_add_u32_e32 v120, 0x13800, v199
	s_waitcnt lgkmcnt(1)
	v_mfma_f32_16x16x32_bf16 v[112:115], v[44:47], v[112:115], 0
	s_waitcnt lgkmcnt(0)
	v_mfma_f32_16x16x32_bf16 v[112:115], v[48:51], v[116:119], v[112:115]
	ds_read_b128 v[116:119], v120
	v_add_u32_e32 v120, 0x13c00, v199
	ds_read_b128 v[120:123], v120
	s_waitcnt lgkmcnt(1)
	v_mfma_f32_16x16x32_bf16 v[112:115], v[52:55], v[116:119], v[112:115]
	v_add_u32_e32 v116, 0x14000, v199
	s_waitcnt lgkmcnt(0)
	v_mfma_f32_16x16x32_bf16 v[136:139], v[60:63], v[120:123], v[112:115]
	v_add_u32_e32 v120, 0x14800, v199
	s_nop 3
	ds_read_b128 v[112:115], v116
	v_add_u32_e32 v116, 0x14400, v199
	ds_read_b128 v[116:119], v116
	s_waitcnt lgkmcnt(1)
	v_mfma_f32_16x16x32_bf16 v[112:115], v[44:47], v[112:115], 0
	s_waitcnt lgkmcnt(0)
	v_mfma_f32_16x16x32_bf16 v[112:115], v[48:51], v[116:119], v[112:115]
	ds_read_b128 v[116:119], v120
	v_add_u32_e32 v120, 0x14c00, v199
	s_waitcnt lgkmcnt(0)
	v_mfma_f32_16x16x32_bf16 v[112:115], v[52:55], v[116:119], v[112:115]
	ds_read_b128 v[116:119], v120
	s_waitcnt lgkmcnt(0)
	v_mfma_f32_16x16x32_bf16 v[140:143], v[60:63], v[116:119], v[112:115]
	s_nop 4
	v_add_u32_e32 v112, 0x15000, v199
	ds_read_b128 v[112:115], v112
	v_add_u32_e32 v116, 0x15400, v199
	ds_read_b128 v[116:119], v116
	v_add_u32_e32 v120, 0x15800, v199
	s_waitcnt lgkmcnt(1)
	v_mfma_f32_16x16x32_bf16 v[112:115], v[44:47], v[112:115], 0
	s_waitcnt lgkmcnt(0)
	v_mfma_f32_16x16x32_bf16 v[112:115], v[48:51], v[116:119], v[112:115]
	ds_read_b128 v[116:119], v120
	v_add_u32_e32 v120, 0x15c00, v199
	ds_read_b128 v[120:123], v120
	s_waitcnt lgkmcnt(1)
	v_mfma_f32_16x16x32_bf16 v[112:115], v[52:55], v[116:119], v[112:115]
	v_add_u32_e32 v116, 0x16000, v199
	s_waitcnt lgkmcnt(0)
	v_mfma_f32_16x16x32_bf16 v[124:127], v[60:63], v[120:123], v[112:115]
	v_add_u32_e32 v120, 0x16800, v199
	s_nop 3
	ds_read_b128 v[112:115], v116
	v_add_u32_e32 v116, 0x16400, v199
	ds_read_b128 v[116:119], v116
	s_waitcnt lgkmcnt(1)
	v_mfma_f32_16x16x32_bf16 v[112:115], v[44:47], v[112:115], 0
	s_waitcnt lgkmcnt(0)
	v_mfma_f32_16x16x32_bf16 v[112:115], v[48:51], v[116:119], v[112:115]
	ds_read_b128 v[116:119], v120
	v_add_u32_e32 v120, 0x16c00, v199
	s_waitcnt lgkmcnt(0)
	v_mfma_f32_16x16x32_bf16 v[112:115], v[52:55], v[116:119], v[112:115]
	ds_read_b128 v[116:119], v120
	s_waitcnt lgkmcnt(0)
	v_mfma_f32_16x16x32_bf16 v[132:135], v[60:63], v[116:119], v[112:115]
	s_nop 4
	v_add_u32_e32 v112, 0x17000, v199
	ds_read_b128 v[112:115], v112
	v_add_u32_e32 v116, 0x17400, v199
	ds_read_b128 v[116:119], v116
	v_add_u32_e32 v120, 0x17800, v199
	v_add_u32_e32 v128, 0x18000, v199
	s_waitcnt lgkmcnt(1)
	v_mfma_f32_16x16x32_bf16 v[112:115], v[44:47], v[112:115], 0
	s_waitcnt lgkmcnt(0)
	v_mfma_f32_16x16x32_bf16 v[112:115], v[48:51], v[116:119], v[112:115]
	ds_read_b128 v[116:119], v120
	v_add_u32_e32 v120, 0x17c00, v199
	ds_read_b128 v[120:123], v120
	s_waitcnt lgkmcnt(1)
	v_mfma_f32_16x16x32_bf16 v[112:115], v[52:55], v[116:119], v[112:115]
	s_waitcnt lgkmcnt(0)
	v_mfma_f32_16x16x32_bf16 v[116:119], v[60:63], v[120:123], v[112:115]
	v_add_u32_e32 v120, 0x18400, v199
	ds_read_b128 v[120:123], v120
	s_nop 3
	ds_read_b128 v[112:115], v128
	s_waitcnt lgkmcnt(0)
	v_mfma_f32_16x16x32_bf16 v[112:115], v[44:47], v[112:115], 0
	v_add_u32_e32 v128, 0x18800, v199
	v_mfma_f32_16x16x32_bf16 v[112:115], v[48:51], v[120:123], v[112:115]
	ds_read_b128 v[120:123], v128
	v_add_u32_e32 v128, 0x18c00, v199
	s_waitcnt lgkmcnt(0)
	v_mfma_f32_16x16x32_bf16 v[112:115], v[52:55], v[120:123], v[112:115]
	ds_read_b128 v[120:123], v128
	s_waitcnt lgkmcnt(0)
	v_mfma_f32_16x16x32_bf16 v[128:131], v[60:63], v[120:123], v[112:115]
	s_nop 4
	v_add_u32_e32 v112, 0x19000, v199
	ds_read_b128 v[112:115], v112
	v_add_u32_e32 v120, 0x19400, v199
	ds_read_b128 v[120:123], v120
	v_add_u32_e32 v144, 0x19800, v199
	v_add_u32_e32 v148, 0x1a800, v199
	s_waitcnt lgkmcnt(1)
	v_mfma_f32_16x16x32_bf16 v[112:115], v[44:47], v[112:115], 0
	s_waitcnt lgkmcnt(0)
	v_mfma_f32_16x16x32_bf16 v[112:115], v[48:51], v[120:123], v[112:115]
	ds_read_b128 v[120:123], v144
	v_add_u32_e32 v144, 0x19c00, v199
	ds_read_b128 v[144:147], v144
	s_waitcnt lgkmcnt(1)
	v_mfma_f32_16x16x32_bf16 v[112:115], v[52:55], v[120:123], v[112:115]
	v_add_u32_e32 v120, 0x1a000, v199
	ds_read_b128 v[120:123], v120
	s_waitcnt lgkmcnt(1)
	v_mfma_f32_16x16x32_bf16 v[112:115], v[60:63], v[144:147], v[112:115]
	v_add_u32_e32 v144, 0x1a400, v199
	ds_read_b128 v[144:147], v144
	s_waitcnt lgkmcnt(1)
	v_mfma_f32_16x16x32_bf16 v[120:123], v[44:47], v[120:123], 0
	s_waitcnt lgkmcnt(0)
	v_mfma_f32_16x16x32_bf16 v[120:123], v[48:51], v[144:147], v[120:123]
	ds_read_b128 v[144:147], v148
	v_add_u32_e32 v148, 0x1ac00, v199
	s_waitcnt lgkmcnt(0)
	v_mfma_f32_16x16x32_bf16 v[120:123], v[52:55], v[144:147], v[120:123]
	ds_read_b128 v[144:147], v148
	s_waitcnt lgkmcnt(0)
	v_mfma_f32_16x16x32_bf16 v[120:123], v[60:63], v[144:147], v[120:123]
	s_waitcnt lgkmcnt(0)
	s_barrier
	ds_write_b128 v220, v[64:67]
	ds_write_b128 v221, v[68:71]
	ds_write_b128 v221, v[72:75] offset:8704
	ds_write_b128 v221, v[76:79] offset:17408
	ds_read_b128 v[64:67], v199
	ds_read_b128 v[68:71], v199 offset:1024
	s_waitcnt lgkmcnt(1)
	v_mfma_f32_16x16x32_bf16 v[64:67], v[44:47], v[64:67], 0
	s_waitcnt lgkmcnt(0)
	v_mfma_f32_16x16x32_bf16 v[64:67], v[48:51], v[68:71], v[64:67]
	ds_read_b128 v[68:71], v199 offset:2048
	ds_read_b128 v[72:75], v199 offset:3072
	s_waitcnt lgkmcnt(1)
	v_mfma_f32_16x16x32_bf16 v[64:67], v[52:55], v[68:71], v[64:67]
	ds_read_b128 v[68:71], v199 offset:5120
	s_waitcnt lgkmcnt(1)
	v_mfma_f32_16x16x32_bf16 v[152:155], v[60:63], v[72:75], v[64:67]
	s_nop 4
	ds_read_b128 v[64:67], v199 offset:4096
	s_waitcnt lgkmcnt(0)
	v_mfma_f32_16x16x32_bf16 v[64:67], v[44:47], v[64:67], 0
	v_mfma_f32_16x16x32_bf16 v[64:67], v[48:51], v[68:71], v[64:67]
	ds_read_b128 v[68:71], v199 offset:6144
	s_waitcnt lgkmcnt(0)
	v_mfma_f32_16x16x32_bf16 v[64:67], v[52:55], v[68:71], v[64:67]
	ds_read_b128 v[68:71], v199 offset:7168
	s_waitcnt lgkmcnt(0)
	v_mfma_f32_16x16x32_bf16 v[156:159], v[60:63], v[68:71], v[64:67]
	s_nop 4
	ds_read_b128 v[64:67], v199 offset:8192
	ds_read_b128 v[68:71], v199 offset:9216
	s_waitcnt lgkmcnt(1)
	v_mfma_f32_16x16x32_bf16 v[64:67], v[44:47], v[64:67], 0
	s_waitcnt lgkmcnt(0)
	v_mfma_f32_16x16x32_bf16 v[64:67], v[48:51], v[68:71], v[64:67]
	ds_read_b128 v[68:71], v199 offset:10240
	ds_read_b128 v[72:75], v199 offset:11264
	s_waitcnt lgkmcnt(1)
	v_mfma_f32_16x16x32_bf16 v[64:67], v[52:55], v[68:71], v[64:67]
	ds_read_b128 v[68:71], v199 offset:13312
	s_waitcnt lgkmcnt(1)
	v_mfma_f32_16x16x32_bf16 v[144:147], v[60:63], v[72:75], v[64:67]
	s_nop 4
	ds_read_b128 v[64:67], v199 offset:12288
	s_waitcnt lgkmcnt(0)
	v_mfma_f32_16x16x32_bf16 v[64:67], v[44:47], v[64:67], 0
	v_mfma_f32_16x16x32_bf16 v[64:67], v[48:51], v[68:71], v[64:67]
	ds_read_b128 v[68:71], v199 offset:14336
	s_waitcnt lgkmcnt(0)
	v_mfma_f32_16x16x32_bf16 v[64:67], v[52:55], v[68:71], v[64:67]
	ds_read_b128 v[68:71], v199 offset:15360
	s_waitcnt lgkmcnt(0)
	v_mfma_f32_16x16x32_bf16 v[148:151], v[60:63], v[68:71], v[64:67]
	s_nop 4
	ds_read_b128 v[64:67], v199 offset:16384
	ds_read_b128 v[68:71], v199 offset:17408
	s_waitcnt lgkmcnt(1)
	v_mfma_f32_16x16x32_bf16 v[64:67], v[44:47], v[64:67], 0
	s_waitcnt lgkmcnt(0)
	v_mfma_f32_16x16x32_bf16 v[64:67], v[48:51], v[68:71], v[64:67]
	ds_read_b128 v[68:71], v199 offset:18432
	ds_read_b128 v[72:75], v199 offset:19456
	s_waitcnt lgkmcnt(1)
	v_mfma_f32_16x16x32_bf16 v[64:67], v[52:55], v[68:71], v[64:67]
	ds_read_b128 v[68:71], v199 offset:21504
	s_waitcnt lgkmcnt(1)
	v_mfma_f32_16x16x32_bf16 v[72:75], v[60:63], v[72:75], v[64:67]
	s_nop 4
	ds_read_b128 v[64:67], v199 offset:20480
	s_waitcnt lgkmcnt(0)
	v_mfma_f32_16x16x32_bf16 v[64:67], v[44:47], v[64:67], 0
	v_mfma_f32_16x16x32_bf16 v[64:67], v[48:51], v[68:71], v[64:67]
	ds_read_b128 v[68:71], v199 offset:22528
	s_waitcnt lgkmcnt(0)
	v_mfma_f32_16x16x32_bf16 v[64:67], v[52:55], v[68:71], v[64:67]
	ds_read_b128 v[68:71], v199 offset:23552
	s_waitcnt lgkmcnt(0)
	v_mfma_f32_16x16x32_bf16 v[76:79], v[60:63], v[68:71], v[64:67]
	s_nop 4
	ds_read_b128 v[64:67], v199 offset:24576
	ds_read_b128 v[68:71], v199 offset:25600
	s_waitcnt lgkmcnt(1)
	v_mfma_f32_16x16x32_bf16 v[64:67], v[44:47], v[64:67], 0
	s_waitcnt lgkmcnt(0)
	v_mfma_f32_16x16x32_bf16 v[64:67], v[48:51], v[68:71], v[64:67]
	ds_read_b128 v[68:71], v199 offset:26624
	ds_read_b128 v[236:239], v199 offset:27648
	s_waitcnt lgkmcnt(1)
	v_mfma_f32_16x16x32_bf16 v[64:67], v[52:55], v[68:71], v[64:67]
	ds_read_b128 v[68:71], v199 offset:28672
	s_waitcnt lgkmcnt(1)
	v_mfma_f32_16x16x32_bf16 v[64:67], v[60:63], v[236:239], v[64:67]
	ds_read_b128 v[236:239], v199 offset:29696
	s_waitcnt lgkmcnt(1)
	v_mfma_f32_16x16x32_bf16 v[68:71], v[44:47], v[68:71], 0
	s_waitcnt lgkmcnt(0)
	v_mfma_f32_16x16x32_bf16 v[68:71], v[48:51], v[236:239], v[68:71]
	ds_read_b128 v[236:239], v199 offset:30720
	s_waitcnt lgkmcnt(0)
	v_mfma_f32_16x16x32_bf16 v[68:71], v[52:55], v[236:239], v[68:71]
	ds_read_b128 v[236:239], v199 offset:31744
	s_waitcnt lgkmcnt(0)
	v_mfma_f32_16x16x32_bf16 v[68:71], v[60:63], v[236:239], v[68:71]
	s_add_i32 s45, s45, s34
	s_cmpk_gt_i32 s45, 0x3ff
	s_cselect_b64 s[16:17], -1, 0
	s_and_b64 vcc, exec, s[16:17]
	s_cbranch_vccnz .LBB0_902
	s_ashr_i32 s48, s45, 7
	s_and_b32 s64, s45, 31
	s_ashr_i32 s49, s48, 31
	s_lshl_b64 s[52:53], s[48:49], 12
	s_lshl_b32 s4, s64, 7
	s_or_b32 s52, s52, s4
	s_mul_i32 s4, s53, 0x1c00
	s_mul_hi_u32 s49, s52, 0x1c00
	s_bfe_u32 s47, s45, 0x20005
	s_add_i32 s49, s49, s4
	s_mul_i32 s4, s52, 0x1c00
	s_add_u32 s62, s0, s4
	s_addc_u32 s49, s1, s49
	s_lshl_b32 s4, s47, 8
	s_add_u32 s62, s62, s4
	s_addc_u32 s63, s49, 0
	s_lshl_b32 s48, s48, 2
	s_ashr_i32 s49, s48, 31
	s_or_b32 s48, s48, s47
	s_lshl_b64 s[48:49], s[48:49], 20
	s_add_u32 s47, s11, s48
	s_addc_u32 s49, s13, s49
	s_lshl_b32 s48, s64, 15
	s_add_u32 s48, s47, s48
	s_addc_u32 s49, s49, 0
	v_mov_b32_e32 v199, v167
	v_lshl_add_u64 v[40:41], s[48:49], 0, v[198:199]
	v_add_co_u32_e32 v16, vcc, s28, v40
	v_lshl_add_u64 v[42:43], s[52:53], 0, v[170:171]
	s_nop 0
	v_addc_co_u32_e32 v17, vcc, 0, v41, vcc
	v_mov_b64_e32 v[44:45], s[0:1]
	v_add_co_u32_e32 v28, vcc, s30, v40
	v_mad_u64_u32 v[44:45], s[52:53], v42, s26, v[44:45]
	v_lshl_add_u64 v[8:9], s[62:63], 0, v[166:167]
	v_addc_co_u32_e32 v29, vcc, 0, v41, vcc
	v_mad_i32_i24 v45, v43, s26, v45
	v_lshl_add_u64 v[32:33], v[8:9], 0, v[196:197]
	v_add_co_u32_e32 v40, vcc, s31, v40
	v_lshl_add_u64 v[42:43], v[44:45], 0, s[4:5]
	v_mov_b32_e32 v201, v167
	v_lshl_add_u64 v[4:5], v[8:9], 0, v[194:195]
	v_lshl_add_u64 v[24:25], v[32:33], 0, s[6:7]
	v_lshl_add_u64 v[36:37], v[32:33], 0, s[8:9]
	v_addc_co_u32_e32 v41, vcc, 0, v41, vcc
	v_lshl_add_u64 v[60:61], v[42:43], 0, v[200:201]
	global_load_dwordx4 v[0:3], v[4:5], off offset:1024
	s_nop 0
	global_load_dwordx4 v[4:7], v[4:5], off offset:2048
	s_nop 0
	global_load_dwordx4 v[8:11], v[32:33], off offset:1024
	global_load_dwordx4 v[12:15], v[32:33], off offset:2048
	s_nop 0
	global_load_dwordx4 v[16:19], v[16:17], off
	s_nop 0
	global_load_dwordx4 v[20:23], v[24:25], off offset:1024
	s_nop 0
	global_load_dwordx4 v[24:27], v[24:25], off offset:2048
	s_nop 0
	global_load_dwordx4 v[28:31], v[28:29], off
	s_nop 0
	global_load_dwordx4 v[32:35], v[36:37], off offset:1024
	s_nop 0
	global_load_dwordx4 v[36:39], v[36:37], off offset:2048
	s_nop 0
	global_load_dwordx4 v[40:43], v[40:41], off
	s_nop 0
	global_load_dwordx4 v[44:47], v[60:61], off
	global_load_dwordx4 v[48:51], v[60:61], off offset:64
	global_load_dwordx4 v[52:55], v[60:61], off offset:128
	global_load_dwordx4 v[56:59], v198, s[48:49]
	s_nop 0
	global_load_dwordx4 v[60:63], v[60:61], off offset:192
	s_branch .LBB0_902
